# P6 (proj_b/proj_a GEMM) epilogues rewritten: all gate/prev loads issued ahead with counted vmcnt, stores deferred to the end
# speedup vs baseline: 1.0109x; 1.0109x over previous
.LBB0_505:
	v_lshl_add_u32 v148, s58, 8, v161
	v_lshl_or_b32 v149, s59, 8, v163
	v_lshlrev_b32_e32 v149, 1, v149
	v_lshl_add_u32 v146, v148, 11, v149
	v_lshl_add_u32 v147, v148, 12, v149
	s_and_b64 vcc, exec, s[2:3]
	s_mov_b64 s[2:3], -1
	s_add_u32 s70, s12, 0x800
	s_addc_u32 s71, s13, 0
	global_load_dwordx4 v[168:171], v147, s[70:71] offset:0
	global_load_dwordx4 v[172:175], v147, s[70:71] offset:256
	s_add_u32 s70, s12, 0x10800
	s_addc_u32 s71, s13, 0
	global_load_dwordx4 v[176:179], v147, s[70:71] offset:0
	global_load_dwordx4 v[180:183], v147, s[70:71] offset:256
	s_add_u32 s70, s12, 0x20800
	s_addc_u32 s71, s13, 0
	global_load_dwordx4 v[184:187], v147, s[70:71] offset:0
	global_load_dwordx4 v[188:191], v147, s[70:71] offset:256
	s_add_u32 s70, s12, 0x30800
	s_addc_u32 s71, s13, 0
	global_load_dwordx4 v[192:195], v147, s[70:71] offset:0
	global_load_dwordx4 v[196:199], v147, s[70:71] offset:256
	s_add_u32 s70, s12, 0x80800
	s_addc_u32 s71, s13, 0
	global_load_dwordx4 v[200:203], v147, s[70:71] offset:0
	global_load_dwordx4 v[204:207], v147, s[70:71] offset:256
	s_add_u32 s70, s12, 0x90800
	s_addc_u32 s71, s13, 0
	global_load_dwordx4 v[208:211], v147, s[70:71] offset:0
	global_load_dwordx4 v[212:215], v147, s[70:71] offset:256
	s_add_u32 s70, s12, 0xa0800
	s_addc_u32 s71, s13, 0
	global_load_dwordx4 v[216:219], v147, s[70:71] offset:0
	global_load_dwordx4 v[220:223], v147, s[70:71] offset:256
	s_add_u32 s70, s12, 0xb0800
	s_addc_u32 s71, s13, 0
	global_load_dwordx4 v[224:227], v147, s[70:71] offset:0
	global_load_dwordx4 v[246:249], v147, s[70:71] offset:256
	s_waitcnt vmcnt(15)
	v_lshlrev_b32_e32 v242, 16, v168
	v_and_b32_e32 v243, 0xffff0000, v168
	v_mul_f32_e32 v126, v126, v242
	v_mul_f32_e32 v127, v127, v243
	v_lshlrev_b32_e32 v242, 16, v169
	v_and_b32_e32 v243, 0xffff0000, v169
	v_mul_f32_e32 v128, v128, v242
	v_mul_f32_e32 v129, v129, v243
	v_lshlrev_b32_e32 v242, 16, v170
	v_and_b32_e32 v243, 0xffff0000, v170
	v_mul_f32_e32 v122, v122, v242
	v_mul_f32_e32 v123, v123, v243
	v_lshlrev_b32_e32 v242, 16, v171
	v_and_b32_e32 v243, 0xffff0000, v171
	v_mul_f32_e32 v124, v124, v242
	v_mul_f32_e32 v125, v125, v243
	v_cvt_pk_bf16_f32 v126, v126, v127
	v_cvt_pk_bf16_f32 v127, v128, v129
	v_cvt_pk_bf16_f32 v128, v122, v123
	v_cvt_pk_bf16_f32 v129, v124, v125
	s_waitcnt vmcnt(14)
	v_lshlrev_b32_e32 v242, 16, v172
	v_and_b32_e32 v243, 0xffff0000, v172
	v_mul_f32_e32 v118, v118, v242
	v_mul_f32_e32 v119, v119, v243
	v_lshlrev_b32_e32 v242, 16, v173
	v_and_b32_e32 v243, 0xffff0000, v173
	v_mul_f32_e32 v120, v120, v242
	v_mul_f32_e32 v121, v121, v243
	v_lshlrev_b32_e32 v242, 16, v174
	v_and_b32_e32 v243, 0xffff0000, v174
	v_mul_f32_e32 v114, v114, v242
	v_mul_f32_e32 v115, v115, v243
	v_lshlrev_b32_e32 v242, 16, v175
	v_and_b32_e32 v243, 0xffff0000, v175
	v_mul_f32_e32 v116, v116, v242
	v_mul_f32_e32 v117, v117, v243
	v_cvt_pk_bf16_f32 v118, v118, v119
	v_cvt_pk_bf16_f32 v119, v120, v121
	v_cvt_pk_bf16_f32 v120, v114, v115
	v_cvt_pk_bf16_f32 v121, v116, v117
	s_waitcnt vmcnt(13)
	v_lshlrev_b32_e32 v242, 16, v176
	v_and_b32_e32 v243, 0xffff0000, v176
	v_mul_f32_e32 v110, v110, v242
	v_mul_f32_e32 v111, v111, v243
	v_lshlrev_b32_e32 v242, 16, v177
	v_and_b32_e32 v243, 0xffff0000, v177
	v_mul_f32_e32 v112, v112, v242
	v_mul_f32_e32 v113, v113, v243
	v_lshlrev_b32_e32 v242, 16, v178
	v_and_b32_e32 v243, 0xffff0000, v178
	v_mul_f32_e32 v106, v106, v242
	v_mul_f32_e32 v107, v107, v243
	v_lshlrev_b32_e32 v242, 16, v179
	v_and_b32_e32 v243, 0xffff0000, v179
	v_mul_f32_e32 v108, v108, v242
	v_mul_f32_e32 v109, v109, v243
	v_cvt_pk_bf16_f32 v110, v110, v111
	v_cvt_pk_bf16_f32 v111, v112, v113
	v_cvt_pk_bf16_f32 v112, v106, v107
	v_cvt_pk_bf16_f32 v113, v108, v109
	s_waitcnt vmcnt(12)
	v_lshlrev_b32_e32 v242, 16, v180
	v_and_b32_e32 v243, 0xffff0000, v180
	v_mul_f32_e32 v102, v102, v242
	v_mul_f32_e32 v103, v103, v243
	v_lshlrev_b32_e32 v242, 16, v181
	v_and_b32_e32 v243, 0xffff0000, v181
	v_mul_f32_e32 v104, v104, v242
	v_mul_f32_e32 v105, v105, v243
	v_lshlrev_b32_e32 v242, 16, v182
	v_and_b32_e32 v243, 0xffff0000, v182
	v_mul_f32_e32 v98, v98, v242
	v_mul_f32_e32 v99, v99, v243
	v_lshlrev_b32_e32 v242, 16, v183
	v_and_b32_e32 v243, 0xffff0000, v183
	v_mul_f32_e32 v100, v100, v242
	v_mul_f32_e32 v101, v101, v243
	v_cvt_pk_bf16_f32 v102, v102, v103
	v_cvt_pk_bf16_f32 v103, v104, v105
	v_cvt_pk_bf16_f32 v104, v98, v99
	v_cvt_pk_bf16_f32 v105, v100, v101
	s_waitcnt vmcnt(11)
	v_lshlrev_b32_e32 v242, 16, v184
	v_and_b32_e32 v243, 0xffff0000, v184
	v_mul_f32_e32 v94, v94, v242
	v_mul_f32_e32 v95, v95, v243
	v_lshlrev_b32_e32 v242, 16, v185
	v_and_b32_e32 v243, 0xffff0000, v185
	v_mul_f32_e32 v96, v96, v242
	v_mul_f32_e32 v97, v97, v243
	v_lshlrev_b32_e32 v242, 16, v186
	v_and_b32_e32 v243, 0xffff0000, v186
	v_mul_f32_e32 v90, v90, v242
	v_mul_f32_e32 v91, v91, v243
	v_lshlrev_b32_e32 v242, 16, v187
	v_and_b32_e32 v243, 0xffff0000, v187
	v_mul_f32_e32 v92, v92, v242
	v_mul_f32_e32 v93, v93, v243
	v_cvt_pk_bf16_f32 v94, v94, v95
	v_cvt_pk_bf16_f32 v95, v96, v97
	v_cvt_pk_bf16_f32 v96, v90, v91
	v_cvt_pk_bf16_f32 v97, v92, v93
	s_waitcnt vmcnt(10)
	v_lshlrev_b32_e32 v242, 16, v188
	v_and_b32_e32 v243, 0xffff0000, v188
	v_mul_f32_e32 v86, v86, v242
	v_mul_f32_e32 v87, v87, v243
	v_lshlrev_b32_e32 v242, 16, v189
	v_and_b32_e32 v243, 0xffff0000, v189
	v_mul_f32_e32 v88, v88, v242
	v_mul_f32_e32 v89, v89, v243
	v_lshlrev_b32_e32 v242, 16, v190
	v_and_b32_e32 v243, 0xffff0000, v190
	v_mul_f32_e32 v82, v82, v242
	v_mul_f32_e32 v83, v83, v243
	v_lshlrev_b32_e32 v242, 16, v191
	v_and_b32_e32 v243, 0xffff0000, v191
	v_mul_f32_e32 v84, v84, v242
	v_mul_f32_e32 v85, v85, v243
	v_cvt_pk_bf16_f32 v86, v86, v87
	v_cvt_pk_bf16_f32 v87, v88, v89
	v_cvt_pk_bf16_f32 v88, v82, v83
	v_cvt_pk_bf16_f32 v89, v84, v85
	s_waitcnt vmcnt(9)
	v_lshlrev_b32_e32 v242, 16, v192
	v_and_b32_e32 v243, 0xffff0000, v192
	v_mul_f32_e32 v78, v78, v242
	v_mul_f32_e32 v79, v79, v243
	v_lshlrev_b32_e32 v242, 16, v193
	v_and_b32_e32 v243, 0xffff0000, v193
	v_mul_f32_e32 v80, v80, v242
	v_mul_f32_e32 v81, v81, v243
	v_lshlrev_b32_e32 v242, 16, v194
	v_and_b32_e32 v243, 0xffff0000, v194
	v_mul_f32_e32 v74, v74, v242
	v_mul_f32_e32 v75, v75, v243
	v_lshlrev_b32_e32 v242, 16, v195
	v_and_b32_e32 v243, 0xffff0000, v195
	v_mul_f32_e32 v76, v76, v242
	v_mul_f32_e32 v77, v77, v243
	v_cvt_pk_bf16_f32 v78, v78, v79
	v_cvt_pk_bf16_f32 v79, v80, v81
	v_cvt_pk_bf16_f32 v80, v74, v75
	v_cvt_pk_bf16_f32 v81, v76, v77
	s_waitcnt vmcnt(8)
	v_lshlrev_b32_e32 v242, 16, v196
	v_and_b32_e32 v243, 0xffff0000, v196
	v_mul_f32_e32 v70, v70, v242
	v_mul_f32_e32 v71, v71, v243
	v_lshlrev_b32_e32 v242, 16, v197
	v_and_b32_e32 v243, 0xffff0000, v197
	v_mul_f32_e32 v72, v72, v242
	v_mul_f32_e32 v73, v73, v243
	v_lshlrev_b32_e32 v242, 16, v198
	v_and_b32_e32 v243, 0xffff0000, v198
	v_mul_f32_e32 v66, v66, v242
	v_mul_f32_e32 v67, v67, v243
	v_lshlrev_b32_e32 v242, 16, v199
	v_and_b32_e32 v243, 0xffff0000, v199
	v_mul_f32_e32 v68, v68, v242
	v_mul_f32_e32 v69, v69, v243
	v_cvt_pk_bf16_f32 v70, v70, v71
	v_cvt_pk_bf16_f32 v71, v72, v73
	v_cvt_pk_bf16_f32 v72, v66, v67
	v_cvt_pk_bf16_f32 v73, v68, v69
	s_waitcnt vmcnt(7)
	v_lshlrev_b32_e32 v242, 16, v200
	v_and_b32_e32 v243, 0xffff0000, v200
	v_mul_f32_e32 v62, v62, v242
	v_mul_f32_e32 v63, v63, v243
	v_lshlrev_b32_e32 v242, 16, v201
	v_and_b32_e32 v243, 0xffff0000, v201
	v_mul_f32_e32 v64, v64, v242
	v_mul_f32_e32 v65, v65, v243
	v_lshlrev_b32_e32 v242, 16, v202
	v_and_b32_e32 v243, 0xffff0000, v202
	v_mul_f32_e32 v58, v58, v242
	v_mul_f32_e32 v59, v59, v243
	v_lshlrev_b32_e32 v242, 16, v203
	v_and_b32_e32 v243, 0xffff0000, v203
	v_mul_f32_e32 v60, v60, v242
	v_mul_f32_e32 v61, v61, v243
	v_cvt_pk_bf16_f32 v62, v62, v63
	v_cvt_pk_bf16_f32 v63, v64, v65
	v_cvt_pk_bf16_f32 v64, v58, v59
	v_cvt_pk_bf16_f32 v65, v60, v61
	s_waitcnt vmcnt(6)
	v_lshlrev_b32_e32 v242, 16, v204
	v_and_b32_e32 v243, 0xffff0000, v204
	v_mul_f32_e32 v54, v54, v242
	v_mul_f32_e32 v55, v55, v243
	v_lshlrev_b32_e32 v242, 16, v205
	v_and_b32_e32 v243, 0xffff0000, v205
	v_mul_f32_e32 v56, v56, v242
	v_mul_f32_e32 v57, v57, v243
	v_lshlrev_b32_e32 v242, 16, v206
	v_and_b32_e32 v243, 0xffff0000, v206
	v_mul_f32_e32 v50, v50, v242
	v_mul_f32_e32 v51, v51, v243
	v_lshlrev_b32_e32 v242, 16, v207
	v_and_b32_e32 v243, 0xffff0000, v207
	v_mul_f32_e32 v52, v52, v242
	v_mul_f32_e32 v53, v53, v243
	v_cvt_pk_bf16_f32 v54, v54, v55
	v_cvt_pk_bf16_f32 v55, v56, v57
	v_cvt_pk_bf16_f32 v56, v50, v51
	v_cvt_pk_bf16_f32 v57, v52, v53
	s_waitcnt vmcnt(5)
	v_lshlrev_b32_e32 v242, 16, v208
	v_and_b32_e32 v243, 0xffff0000, v208
	v_mul_f32_e32 v46, v46, v242
	v_mul_f32_e32 v47, v47, v243
	v_lshlrev_b32_e32 v242, 16, v209
	v_and_b32_e32 v243, 0xffff0000, v209
	v_mul_f32_e32 v48, v48, v242
	v_mul_f32_e32 v49, v49, v243
	v_lshlrev_b32_e32 v242, 16, v210
	v_and_b32_e32 v243, 0xffff0000, v210
	v_mul_f32_e32 v42, v42, v242
	v_mul_f32_e32 v43, v43, v243
	v_lshlrev_b32_e32 v242, 16, v211
	v_and_b32_e32 v243, 0xffff0000, v211
	v_mul_f32_e32 v44, v44, v242
	v_mul_f32_e32 v45, v45, v243
	v_cvt_pk_bf16_f32 v46, v46, v47
	v_cvt_pk_bf16_f32 v47, v48, v49
	v_cvt_pk_bf16_f32 v48, v42, v43
	v_cvt_pk_bf16_f32 v49, v44, v45
	s_waitcnt vmcnt(4)
	v_lshlrev_b32_e32 v242, 16, v212
	v_and_b32_e32 v243, 0xffff0000, v212
	v_mul_f32_e32 v38, v38, v242
	v_mul_f32_e32 v39, v39, v243
	v_lshlrev_b32_e32 v242, 16, v213
	v_and_b32_e32 v243, 0xffff0000, v213
	v_mul_f32_e32 v40, v40, v242
	v_mul_f32_e32 v41, v41, v243
	v_lshlrev_b32_e32 v242, 16, v214
	v_and_b32_e32 v243, 0xffff0000, v214
	v_mul_f32_e32 v34, v34, v242
	v_mul_f32_e32 v35, v35, v243
	v_lshlrev_b32_e32 v242, 16, v215
	v_and_b32_e32 v243, 0xffff0000, v215
	v_mul_f32_e32 v36, v36, v242
	v_mul_f32_e32 v37, v37, v243
	v_cvt_pk_bf16_f32 v38, v38, v39
	v_cvt_pk_bf16_f32 v39, v40, v41
	v_cvt_pk_bf16_f32 v40, v34, v35
	v_cvt_pk_bf16_f32 v41, v36, v37
	s_waitcnt vmcnt(3)
	v_lshlrev_b32_e32 v242, 16, v216
	v_and_b32_e32 v243, 0xffff0000, v216
	v_mul_f32_e32 v30, v30, v242
	v_mul_f32_e32 v31, v31, v243
	v_lshlrev_b32_e32 v242, 16, v217
	v_and_b32_e32 v243, 0xffff0000, v217
	v_mul_f32_e32 v32, v32, v242
	v_mul_f32_e32 v33, v33, v243
	v_lshlrev_b32_e32 v242, 16, v218
	v_and_b32_e32 v243, 0xffff0000, v218
	v_mul_f32_e32 v26, v26, v242
	v_mul_f32_e32 v27, v27, v243
	v_lshlrev_b32_e32 v242, 16, v219
	v_and_b32_e32 v243, 0xffff0000, v219
	v_mul_f32_e32 v28, v28, v242
	v_mul_f32_e32 v29, v29, v243
	v_cvt_pk_bf16_f32 v30, v30, v31
	v_cvt_pk_bf16_f32 v31, v32, v33
	v_cvt_pk_bf16_f32 v32, v26, v27
	v_cvt_pk_bf16_f32 v33, v28, v29
	s_waitcnt vmcnt(2)
	v_lshlrev_b32_e32 v242, 16, v220
	v_and_b32_e32 v243, 0xffff0000, v220
	v_mul_f32_e32 v22, v22, v242
	v_mul_f32_e32 v23, v23, v243
	v_lshlrev_b32_e32 v242, 16, v221
	v_and_b32_e32 v243, 0xffff0000, v221
	v_mul_f32_e32 v24, v24, v242
	v_mul_f32_e32 v25, v25, v243
	v_lshlrev_b32_e32 v242, 16, v222
	v_and_b32_e32 v243, 0xffff0000, v222
	v_mul_f32_e32 v18, v18, v242
	v_mul_f32_e32 v19, v19, v243
	v_lshlrev_b32_e32 v242, 16, v223
	v_and_b32_e32 v243, 0xffff0000, v223
	v_mul_f32_e32 v20, v20, v242
	v_mul_f32_e32 v21, v21, v243
	v_cvt_pk_bf16_f32 v22, v22, v23
	v_cvt_pk_bf16_f32 v23, v24, v25
	v_cvt_pk_bf16_f32 v24, v18, v19
	v_cvt_pk_bf16_f32 v25, v20, v21
	s_waitcnt vmcnt(1)
	v_lshlrev_b32_e32 v242, 16, v224
	v_and_b32_e32 v243, 0xffff0000, v224
	v_mul_f32_e32 v14, v14, v242
	v_mul_f32_e32 v15, v15, v243
	v_lshlrev_b32_e32 v242, 16, v225
	v_and_b32_e32 v243, 0xffff0000, v225
	v_mul_f32_e32 v16, v16, v242
	v_mul_f32_e32 v17, v17, v243
	v_lshlrev_b32_e32 v242, 16, v226
	v_and_b32_e32 v243, 0xffff0000, v226
	v_mul_f32_e32 v10, v10, v242
	v_mul_f32_e32 v11, v11, v243
	v_lshlrev_b32_e32 v242, 16, v227
	v_and_b32_e32 v243, 0xffff0000, v227
	v_mul_f32_e32 v12, v12, v242
	v_mul_f32_e32 v13, v13, v243
	v_cvt_pk_bf16_f32 v14, v14, v15
	v_cvt_pk_bf16_f32 v15, v16, v17
	v_cvt_pk_bf16_f32 v16, v10, v11
	v_cvt_pk_bf16_f32 v17, v12, v13
	s_waitcnt vmcnt(0)
	v_lshlrev_b32_e32 v242, 16, v246
	v_and_b32_e32 v243, 0xffff0000, v246
	v_mul_f32_e32 v6, v6, v242
	v_mul_f32_e32 v7, v7, v243
	v_lshlrev_b32_e32 v242, 16, v247
	v_and_b32_e32 v243, 0xffff0000, v247
	v_mul_f32_e32 v8, v8, v242
	v_mul_f32_e32 v9, v9, v243
	v_lshlrev_b32_e32 v242, 16, v248
	v_and_b32_e32 v243, 0xffff0000, v248
	v_mul_f32_e32 v2, v2, v242
	v_mul_f32_e32 v3, v3, v243
	v_lshlrev_b32_e32 v242, 16, v249
	v_and_b32_e32 v243, 0xffff0000, v249
	v_mul_f32_e32 v4, v4, v242
	v_mul_f32_e32 v5, v5, v243
	v_cvt_pk_bf16_f32 v6, v6, v7
	v_cvt_pk_bf16_f32 v7, v8, v9
	v_cvt_pk_bf16_f32 v8, v2, v3
	v_cvt_pk_bf16_f32 v9, v4, v5
	s_add_u32 s72, s6, 0x0
	s_addc_u32 s73, s7, 0
	global_store_dwordx4 v146, v[126:129], s[72:73] offset:0
	global_store_dwordx4 v146, v[118:121], s[72:73] offset:256
	s_add_u32 s72, s6, 0x8000
	s_addc_u32 s73, s7, 0
	global_store_dwordx4 v146, v[110:113], s[72:73] offset:0
	global_store_dwordx4 v146, v[102:105], s[72:73] offset:256
	s_add_u32 s72, s6, 0x10000
	s_addc_u32 s73, s7, 0
	global_store_dwordx4 v146, v[94:97], s[72:73] offset:0
	global_store_dwordx4 v146, v[86:89], s[72:73] offset:256
	s_add_u32 s72, s6, 0x18000
	s_addc_u32 s73, s7, 0
	global_store_dwordx4 v146, v[78:81], s[72:73] offset:0
	global_store_dwordx4 v146, v[70:73], s[72:73] offset:256
	s_add_u32 s72, s6, 0x40000
	s_addc_u32 s73, s7, 0
	global_store_dwordx4 v146, v[62:65], s[72:73] offset:0
	global_store_dwordx4 v146, v[54:57], s[72:73] offset:256
	s_add_u32 s72, s6, 0x48000
	s_addc_u32 s73, s7, 0
	global_store_dwordx4 v146, v[46:49], s[72:73] offset:0
	global_store_dwordx4 v146, v[38:41], s[72:73] offset:256
	s_add_u32 s72, s6, 0x50000
	s_addc_u32 s73, s7, 0
	global_store_dwordx4 v146, v[30:33], s[72:73] offset:0
	global_store_dwordx4 v146, v[22:25], s[72:73] offset:256
	s_add_u32 s72, s6, 0x58000
	s_addc_u32 s73, s7, 0
	global_store_dwordx4 v146, v[14:17], s[72:73] offset:0
	global_store_dwordx4 v146, v[6:9], s[72:73] offset:256
	s_cbranch_vccnz .LBB0_489
	s_andn2_b64 vcc, exec, s[22:23]
	s_cbranch_vccnz .LBB0_488
	s_barrier
	s_branch .LBB0_488

.LBB0_531:
	v_lshl_add_u32 v148, s49, 8, v155
	v_lshl_or_b32 v149, s50, 8, v151
	v_lshlrev_b32_e32 v149, 1, v149
	v_lshl_add_u32 v146, v148, 11, v149
	v_lshl_add_u32 v147, v148, 12, v149
	s_and_b64 vcc, exec, s[2:3]
	s_mov_b64 s[2:3], -1
	s_add_u32 s70, s12, 0x0
	s_addc_u32 s71, s13, 0
	s_add_u32 s72, s6, 0x0
	s_addc_u32 s73, s7, 0
	global_load_dwordx4 v[156:159], v147, s[70:71] offset:0
	global_load_dwordx4 v[160:163], v146, s[72:73] offset:0
	global_load_dwordx4 v[164:167], v147, s[70:71] offset:256
	global_load_dwordx4 v[168:171], v146, s[72:73] offset:256
	s_add_u32 s70, s12, 0x10000
	s_addc_u32 s71, s13, 0
	s_add_u32 s72, s6, 0x8000
	s_addc_u32 s73, s7, 0
	global_load_dwordx4 v[172:175], v147, s[70:71] offset:0
	global_load_dwordx4 v[176:179], v146, s[72:73] offset:0
	global_load_dwordx4 v[180:183], v147, s[70:71] offset:256
	global_load_dwordx4 v[184:187], v146, s[72:73] offset:256
	s_add_u32 s70, s12, 0x20000
	s_addc_u32 s71, s13, 0
	s_add_u32 s72, s6, 0x10000
	s_addc_u32 s73, s7, 0
	global_load_dwordx4 v[188:191], v147, s[70:71] offset:0
	global_load_dwordx4 v[192:195], v146, s[72:73] offset:0
	global_load_dwordx4 v[196:199], v147, s[70:71] offset:256
	global_load_dwordx4 v[200:203], v146, s[72:73] offset:256
	s_add_u32 s70, s12, 0x30000
	s_addc_u32 s71, s13, 0
	s_add_u32 s72, s6, 0x18000
	s_addc_u32 s73, s7, 0
	global_load_dwordx4 v[204:207], v147, s[70:71] offset:0
	global_load_dwordx4 v[208:211], v146, s[72:73] offset:0
	global_load_dwordx4 v[212:215], v147, s[70:71] offset:256
	global_load_dwordx4 v[226:229], v146, s[72:73] offset:256
	s_add_u32 s70, s12, 0x80000
	s_addc_u32 s71, s13, 0
	s_add_u32 s72, s6, 0x40000
	s_addc_u32 s73, s7, 0
	global_load_dwordx4 v[230:233], v147, s[70:71] offset:0
	global_load_dwordx4 v[234:237], v146, s[72:73] offset:0
	global_load_dwordx4 v[238:241], v147, s[70:71] offset:256
	global_load_dwordx4 v[246:249], v146, s[72:73] offset:256
	s_waitcnt vmcnt(18)
	v_lshlrev_b32_e32 v242, 16, v156
	v_and_b32_e32 v243, 0xffff0000, v156
	v_lshlrev_b32_e32 v244, 16, v160
	v_and_b32_e32 v254, 0xffff0000, v160
	v_fma_f32 v126, v126, v242, v244
	v_fma_f32 v127, v127, v243, v254
	v_lshlrev_b32_e32 v242, 16, v157
	v_and_b32_e32 v243, 0xffff0000, v157
	v_lshlrev_b32_e32 v244, 16, v161
	v_and_b32_e32 v254, 0xffff0000, v161
	v_fma_f32 v128, v128, v242, v244
	v_fma_f32 v129, v129, v243, v254
	v_lshlrev_b32_e32 v242, 16, v158
	v_and_b32_e32 v243, 0xffff0000, v158
	v_lshlrev_b32_e32 v244, 16, v162
	v_and_b32_e32 v254, 0xffff0000, v162
	v_fma_f32 v122, v122, v242, v244
	v_fma_f32 v123, v123, v243, v254
	v_lshlrev_b32_e32 v242, 16, v159
	v_and_b32_e32 v243, 0xffff0000, v159
	v_lshlrev_b32_e32 v244, 16, v163
	v_and_b32_e32 v254, 0xffff0000, v163
	v_fma_f32 v124, v124, v242, v244
	v_fma_f32 v125, v125, v243, v254
	v_cvt_pk_bf16_f32 v126, v126, v127
	v_cvt_pk_bf16_f32 v127, v128, v129
	v_cvt_pk_bf16_f32 v128, v122, v123
	v_cvt_pk_bf16_f32 v129, v124, v125
	s_add_u32 s70, s12, 0x90000
	s_addc_u32 s71, s13, 0
	s_add_u32 s72, s6, 0x48000
	s_addc_u32 s73, s7, 0
	global_load_dwordx4 v[250:253], v147, s[70:71] offset:0
	global_load_dwordx4 v[156:159], v146, s[72:73] offset:0
	s_waitcnt vmcnt(18)
	v_lshlrev_b32_e32 v242, 16, v164
	v_and_b32_e32 v243, 0xffff0000, v164
	v_lshlrev_b32_e32 v244, 16, v168
	v_and_b32_e32 v254, 0xffff0000, v168
	v_fma_f32 v118, v118, v242, v244
	v_fma_f32 v119, v119, v243, v254
	v_lshlrev_b32_e32 v242, 16, v165
	v_and_b32_e32 v243, 0xffff0000, v165
	v_lshlrev_b32_e32 v244, 16, v169
	v_and_b32_e32 v254, 0xffff0000, v169
	v_fma_f32 v120, v120, v242, v244
	v_fma_f32 v121, v121, v243, v254
	v_lshlrev_b32_e32 v242, 16, v166
	v_and_b32_e32 v243, 0xffff0000, v166
	v_lshlrev_b32_e32 v244, 16, v170
	v_and_b32_e32 v254, 0xffff0000, v170
	v_fma_f32 v114, v114, v242, v244
	v_fma_f32 v115, v115, v243, v254
	v_lshlrev_b32_e32 v242, 16, v167
	v_and_b32_e32 v243, 0xffff0000, v167
	v_lshlrev_b32_e32 v244, 16, v171
	v_and_b32_e32 v254, 0xffff0000, v171
	v_fma_f32 v116, v116, v242, v244
	v_fma_f32 v117, v117, v243, v254
	v_cvt_pk_bf16_f32 v118, v118, v119
	v_cvt_pk_bf16_f32 v119, v120, v121
	v_cvt_pk_bf16_f32 v120, v114, v115
	v_cvt_pk_bf16_f32 v121, v116, v117
	global_load_dwordx4 v[160:163], v147, s[70:71] offset:256
	global_load_dwordx4 v[122:125], v146, s[72:73] offset:256
	s_waitcnt vmcnt(18)
	v_lshlrev_b32_e32 v242, 16, v172
	v_and_b32_e32 v243, 0xffff0000, v172
	v_lshlrev_b32_e32 v244, 16, v176
	v_and_b32_e32 v254, 0xffff0000, v176
	v_fma_f32 v110, v110, v242, v244
	v_fma_f32 v111, v111, v243, v254
	v_lshlrev_b32_e32 v242, 16, v173
	v_and_b32_e32 v243, 0xffff0000, v173
	v_lshlrev_b32_e32 v244, 16, v177
	v_and_b32_e32 v254, 0xffff0000, v177
	v_fma_f32 v112, v112, v242, v244
	v_fma_f32 v113, v113, v243, v254
	v_lshlrev_b32_e32 v242, 16, v174
	v_and_b32_e32 v243, 0xffff0000, v174
	v_lshlrev_b32_e32 v244, 16, v178
	v_and_b32_e32 v254, 0xffff0000, v178
	v_fma_f32 v106, v106, v242, v244
	v_fma_f32 v107, v107, v243, v254
	v_lshlrev_b32_e32 v242, 16, v175
	v_and_b32_e32 v243, 0xffff0000, v175
	v_lshlrev_b32_e32 v244, 16, v179
	v_and_b32_e32 v254, 0xffff0000, v179
	v_fma_f32 v108, v108, v242, v244
	v_fma_f32 v109, v109, v243, v254
	v_cvt_pk_bf16_f32 v110, v110, v111
	v_cvt_pk_bf16_f32 v111, v112, v113
	v_cvt_pk_bf16_f32 v112, v106, v107
	v_cvt_pk_bf16_f32 v113, v108, v109
	s_add_u32 s70, s12, 0xa0000
	s_addc_u32 s71, s13, 0
	s_add_u32 s72, s6, 0x50000
	s_addc_u32 s73, s7, 0
	global_load_dwordx4 v[164:167], v147, s[70:71] offset:0
	global_load_dwordx4 v[168:171], v146, s[72:73] offset:0
	s_waitcnt vmcnt(18)
	v_lshlrev_b32_e32 v242, 16, v180
	v_and_b32_e32 v243, 0xffff0000, v180
	v_lshlrev_b32_e32 v244, 16, v184
	v_and_b32_e32 v254, 0xffff0000, v184
	v_fma_f32 v102, v102, v242, v244
	v_fma_f32 v103, v103, v243, v254
	v_lshlrev_b32_e32 v242, 16, v181
	v_and_b32_e32 v243, 0xffff0000, v181
	v_lshlrev_b32_e32 v244, 16, v185
	v_and_b32_e32 v254, 0xffff0000, v185
	v_fma_f32 v104, v104, v242, v244
	v_fma_f32 v105, v105, v243, v254
	v_lshlrev_b32_e32 v242, 16, v182
	v_and_b32_e32 v243, 0xffff0000, v182
	v_lshlrev_b32_e32 v244, 16, v186
	v_and_b32_e32 v254, 0xffff0000, v186
	v_fma_f32 v98, v98, v242, v244
	v_fma_f32 v99, v99, v243, v254
	v_lshlrev_b32_e32 v242, 16, v183
	v_and_b32_e32 v243, 0xffff0000, v183
	v_lshlrev_b32_e32 v244, 16, v187
	v_and_b32_e32 v254, 0xffff0000, v187
	v_fma_f32 v100, v100, v242, v244
	v_fma_f32 v101, v101, v243, v254
	v_cvt_pk_bf16_f32 v102, v102, v103
	v_cvt_pk_bf16_f32 v103, v104, v105
	v_cvt_pk_bf16_f32 v104, v98, v99
	v_cvt_pk_bf16_f32 v105, v100, v101
	global_load_dwordx4 v[114:117], v147, s[70:71] offset:256
	global_load_dwordx4 v[172:175], v146, s[72:73] offset:256
	s_waitcnt vmcnt(18)
	v_lshlrev_b32_e32 v242, 16, v188
	v_and_b32_e32 v243, 0xffff0000, v188
	v_lshlrev_b32_e32 v244, 16, v192
	v_and_b32_e32 v254, 0xffff0000, v192
	v_fma_f32 v94, v94, v242, v244
	v_fma_f32 v95, v95, v243, v254
	v_lshlrev_b32_e32 v242, 16, v189
	v_and_b32_e32 v243, 0xffff0000, v189
	v_lshlrev_b32_e32 v244, 16, v193
	v_and_b32_e32 v254, 0xffff0000, v193
	v_fma_f32 v96, v96, v242, v244
	v_fma_f32 v97, v97, v243, v254
	v_lshlrev_b32_e32 v242, 16, v190
	v_and_b32_e32 v243, 0xffff0000, v190
	v_lshlrev_b32_e32 v244, 16, v194
	v_and_b32_e32 v254, 0xffff0000, v194
	v_fma_f32 v90, v90, v242, v244
	v_fma_f32 v91, v91, v243, v254
	v_lshlrev_b32_e32 v242, 16, v191
	v_and_b32_e32 v243, 0xffff0000, v191
	v_lshlrev_b32_e32 v244, 16, v195
	v_and_b32_e32 v254, 0xffff0000, v195
	v_fma_f32 v92, v92, v242, v244
	v_fma_f32 v93, v93, v243, v254
	v_cvt_pk_bf16_f32 v94, v94, v95
	v_cvt_pk_bf16_f32 v95, v96, v97
	v_cvt_pk_bf16_f32 v96, v90, v91
	v_cvt_pk_bf16_f32 v97, v92, v93
	s_add_u32 s70, s12, 0xb0000
	s_addc_u32 s71, s13, 0
	s_add_u32 s72, s6, 0x58000
	s_addc_u32 s73, s7, 0
	global_load_dwordx4 v[176:179], v147, s[70:71] offset:0
	global_load_dwordx4 v[106:109], v146, s[72:73] offset:0
	s_waitcnt vmcnt(18)
	v_lshlrev_b32_e32 v242, 16, v196
	v_and_b32_e32 v243, 0xffff0000, v196
	v_lshlrev_b32_e32 v244, 16, v200
	v_and_b32_e32 v254, 0xffff0000, v200
	v_fma_f32 v86, v86, v242, v244
	v_fma_f32 v87, v87, v243, v254
	v_lshlrev_b32_e32 v242, 16, v197
	v_and_b32_e32 v243, 0xffff0000, v197
	v_lshlrev_b32_e32 v244, 16, v201
	v_and_b32_e32 v254, 0xffff0000, v201
	v_fma_f32 v88, v88, v242, v244
	v_fma_f32 v89, v89, v243, v254
	v_lshlrev_b32_e32 v242, 16, v198
	v_and_b32_e32 v243, 0xffff0000, v198
	v_lshlrev_b32_e32 v244, 16, v202
	v_and_b32_e32 v254, 0xffff0000, v202
	v_fma_f32 v82, v82, v242, v244
	v_fma_f32 v83, v83, v243, v254
	v_lshlrev_b32_e32 v242, 16, v199
	v_and_b32_e32 v243, 0xffff0000, v199
	v_lshlrev_b32_e32 v244, 16, v203
	v_and_b32_e32 v254, 0xffff0000, v203
	v_fma_f32 v84, v84, v242, v244
	v_fma_f32 v85, v85, v243, v254
	v_cvt_pk_bf16_f32 v86, v86, v87
	v_cvt_pk_bf16_f32 v87, v88, v89
	v_cvt_pk_bf16_f32 v88, v82, v83
	v_cvt_pk_bf16_f32 v89, v84, v85
	global_load_dwordx4 v[180:183], v147, s[70:71] offset:256
	global_load_dwordx4 v[184:187], v146, s[72:73] offset:256
	s_waitcnt vmcnt(18)
	v_lshlrev_b32_e32 v242, 16, v204
	v_and_b32_e32 v243, 0xffff0000, v204
	v_lshlrev_b32_e32 v244, 16, v208
	v_and_b32_e32 v254, 0xffff0000, v208
	v_fma_f32 v78, v78, v242, v244
	v_fma_f32 v79, v79, v243, v254
	v_lshlrev_b32_e32 v242, 16, v205
	v_and_b32_e32 v243, 0xffff0000, v205
	v_lshlrev_b32_e32 v244, 16, v209
	v_and_b32_e32 v254, 0xffff0000, v209
	v_fma_f32 v80, v80, v242, v244
	v_fma_f32 v81, v81, v243, v254
	v_lshlrev_b32_e32 v242, 16, v206
	v_and_b32_e32 v243, 0xffff0000, v206
	v_lshlrev_b32_e32 v244, 16, v210
	v_and_b32_e32 v254, 0xffff0000, v210
	v_fma_f32 v74, v74, v242, v244
	v_fma_f32 v75, v75, v243, v254
	v_lshlrev_b32_e32 v242, 16, v207
	v_and_b32_e32 v243, 0xffff0000, v207
	v_lshlrev_b32_e32 v244, 16, v211
	v_and_b32_e32 v254, 0xffff0000, v211
	v_fma_f32 v76, v76, v242, v244
	v_fma_f32 v77, v77, v243, v254
	v_cvt_pk_bf16_f32 v78, v78, v79
	v_cvt_pk_bf16_f32 v79, v80, v81
	v_cvt_pk_bf16_f32 v80, v74, v75
	v_cvt_pk_bf16_f32 v81, v76, v77
	s_waitcnt vmcnt(16)
	v_lshlrev_b32_e32 v242, 16, v212
	v_and_b32_e32 v243, 0xffff0000, v212
	v_lshlrev_b32_e32 v244, 16, v226
	v_and_b32_e32 v254, 0xffff0000, v226
	v_fma_f32 v70, v70, v242, v244
	v_fma_f32 v71, v71, v243, v254
	v_lshlrev_b32_e32 v242, 16, v213
	v_and_b32_e32 v243, 0xffff0000, v213
	v_lshlrev_b32_e32 v244, 16, v227
	v_and_b32_e32 v254, 0xffff0000, v227
	v_fma_f32 v72, v72, v242, v244
	v_fma_f32 v73, v73, v243, v254
	v_lshlrev_b32_e32 v242, 16, v214
	v_and_b32_e32 v243, 0xffff0000, v214
	v_lshlrev_b32_e32 v244, 16, v228
	v_and_b32_e32 v254, 0xffff0000, v228
	v_fma_f32 v66, v66, v242, v244
	v_fma_f32 v67, v67, v243, v254
	v_lshlrev_b32_e32 v242, 16, v215
	v_and_b32_e32 v243, 0xffff0000, v215
	v_lshlrev_b32_e32 v244, 16, v229
	v_and_b32_e32 v254, 0xffff0000, v229
	v_fma_f32 v68, v68, v242, v244
	v_fma_f32 v69, v69, v243, v254
	v_cvt_pk_bf16_f32 v70, v70, v71
	v_cvt_pk_bf16_f32 v71, v72, v73
	v_cvt_pk_bf16_f32 v72, v66, v67
	v_cvt_pk_bf16_f32 v73, v68, v69
	s_waitcnt vmcnt(14)
	v_lshlrev_b32_e32 v242, 16, v230
	v_and_b32_e32 v243, 0xffff0000, v230
	v_lshlrev_b32_e32 v244, 16, v234
	v_and_b32_e32 v254, 0xffff0000, v234
	v_fma_f32 v62, v62, v242, v244
	v_fma_f32 v63, v63, v243, v254
	v_lshlrev_b32_e32 v242, 16, v231
	v_and_b32_e32 v243, 0xffff0000, v231
	v_lshlrev_b32_e32 v244, 16, v235
	v_and_b32_e32 v254, 0xffff0000, v235
	v_fma_f32 v64, v64, v242, v244
	v_fma_f32 v65, v65, v243, v254
	v_lshlrev_b32_e32 v242, 16, v232
	v_and_b32_e32 v243, 0xffff0000, v232
	v_lshlrev_b32_e32 v244, 16, v236
	v_and_b32_e32 v254, 0xffff0000, v236
	v_fma_f32 v58, v58, v242, v244
	v_fma_f32 v59, v59, v243, v254
	v_lshlrev_b32_e32 v242, 16, v233
	v_and_b32_e32 v243, 0xffff0000, v233
	v_lshlrev_b32_e32 v244, 16, v237
	v_and_b32_e32 v254, 0xffff0000, v237
	v_fma_f32 v60, v60, v242, v244
	v_fma_f32 v61, v61, v243, v254
	v_cvt_pk_bf16_f32 v62, v62, v63
	v_cvt_pk_bf16_f32 v63, v64, v65
	v_cvt_pk_bf16_f32 v64, v58, v59
	v_cvt_pk_bf16_f32 v65, v60, v61
	s_waitcnt vmcnt(12)
	v_lshlrev_b32_e32 v242, 16, v238
	v_and_b32_e32 v243, 0xffff0000, v238
	v_lshlrev_b32_e32 v244, 16, v246
	v_and_b32_e32 v254, 0xffff0000, v246
	v_fma_f32 v54, v54, v242, v244
	v_fma_f32 v55, v55, v243, v254
	v_lshlrev_b32_e32 v242, 16, v239
	v_and_b32_e32 v243, 0xffff0000, v239
	v_lshlrev_b32_e32 v244, 16, v247
	v_and_b32_e32 v254, 0xffff0000, v247
	v_fma_f32 v56, v56, v242, v244
	v_fma_f32 v57, v57, v243, v254
	v_lshlrev_b32_e32 v242, 16, v240
	v_and_b32_e32 v243, 0xffff0000, v240
	v_lshlrev_b32_e32 v244, 16, v248
	v_and_b32_e32 v254, 0xffff0000, v248
	v_fma_f32 v50, v50, v242, v244
	v_fma_f32 v51, v51, v243, v254
	v_lshlrev_b32_e32 v242, 16, v241
	v_and_b32_e32 v243, 0xffff0000, v241
	v_lshlrev_b32_e32 v244, 16, v249
	v_and_b32_e32 v254, 0xffff0000, v249
	v_fma_f32 v52, v52, v242, v244
	v_fma_f32 v53, v53, v243, v254
	v_cvt_pk_bf16_f32 v54, v54, v55
	v_cvt_pk_bf16_f32 v55, v56, v57
	v_cvt_pk_bf16_f32 v56, v50, v51
	v_cvt_pk_bf16_f32 v57, v52, v53
	s_waitcnt vmcnt(10)
	v_lshlrev_b32_e32 v242, 16, v250
	v_and_b32_e32 v243, 0xffff0000, v250
	v_lshlrev_b32_e32 v244, 16, v156
	v_and_b32_e32 v254, 0xffff0000, v156
	v_fma_f32 v46, v46, v242, v244
	v_fma_f32 v47, v47, v243, v254
	v_lshlrev_b32_e32 v242, 16, v251
	v_and_b32_e32 v243, 0xffff0000, v251
	v_lshlrev_b32_e32 v244, 16, v157
	v_and_b32_e32 v254, 0xffff0000, v157
	v_fma_f32 v48, v48, v242, v244
	v_fma_f32 v49, v49, v243, v254
	v_lshlrev_b32_e32 v242, 16, v252
	v_and_b32_e32 v243, 0xffff0000, v252
	v_lshlrev_b32_e32 v244, 16, v158
	v_and_b32_e32 v254, 0xffff0000, v158
	v_fma_f32 v42, v42, v242, v244
	v_fma_f32 v43, v43, v243, v254
	v_lshlrev_b32_e32 v242, 16, v253
	v_and_b32_e32 v243, 0xffff0000, v253
	v_lshlrev_b32_e32 v244, 16, v159
	v_and_b32_e32 v254, 0xffff0000, v159
	v_fma_f32 v44, v44, v242, v244
	v_fma_f32 v45, v45, v243, v254
	v_cvt_pk_bf16_f32 v46, v46, v47
	v_cvt_pk_bf16_f32 v47, v48, v49
	v_cvt_pk_bf16_f32 v48, v42, v43
	v_cvt_pk_bf16_f32 v49, v44, v45
	s_waitcnt vmcnt(8)
	v_lshlrev_b32_e32 v242, 16, v160
	v_and_b32_e32 v243, 0xffff0000, v160
	v_lshlrev_b32_e32 v244, 16, v122
	v_and_b32_e32 v254, 0xffff0000, v122
	v_fma_f32 v38, v38, v242, v244
	v_fma_f32 v39, v39, v243, v254
	v_lshlrev_b32_e32 v242, 16, v161
	v_and_b32_e32 v243, 0xffff0000, v161
	v_lshlrev_b32_e32 v244, 16, v123
	v_and_b32_e32 v254, 0xffff0000, v123
	v_fma_f32 v40, v40, v242, v244
	v_fma_f32 v41, v41, v243, v254
	v_lshlrev_b32_e32 v242, 16, v162
	v_and_b32_e32 v243, 0xffff0000, v162
	v_lshlrev_b32_e32 v244, 16, v124
	v_and_b32_e32 v254, 0xffff0000, v124
	v_fma_f32 v34, v34, v242, v244
	v_fma_f32 v35, v35, v243, v254
	v_lshlrev_b32_e32 v242, 16, v163
	v_and_b32_e32 v243, 0xffff0000, v163
	v_lshlrev_b32_e32 v244, 16, v125
	v_and_b32_e32 v254, 0xffff0000, v125
	v_fma_f32 v36, v36, v242, v244
	v_fma_f32 v37, v37, v243, v254
	v_cvt_pk_bf16_f32 v38, v38, v39
	v_cvt_pk_bf16_f32 v39, v40, v41
	v_cvt_pk_bf16_f32 v40, v34, v35
	v_cvt_pk_bf16_f32 v41, v36, v37
	s_waitcnt vmcnt(6)
	v_lshlrev_b32_e32 v242, 16, v164
	v_and_b32_e32 v243, 0xffff0000, v164
	v_lshlrev_b32_e32 v244, 16, v168
	v_and_b32_e32 v254, 0xffff0000, v168
	v_fma_f32 v30, v30, v242, v244
	v_fma_f32 v31, v31, v243, v254
	v_lshlrev_b32_e32 v242, 16, v165
	v_and_b32_e32 v243, 0xffff0000, v165
	v_lshlrev_b32_e32 v244, 16, v169
	v_and_b32_e32 v254, 0xffff0000, v169
	v_fma_f32 v32, v32, v242, v244
	v_fma_f32 v33, v33, v243, v254
	v_lshlrev_b32_e32 v242, 16, v166
	v_and_b32_e32 v243, 0xffff0000, v166
	v_lshlrev_b32_e32 v244, 16, v170
	v_and_b32_e32 v254, 0xffff0000, v170
	v_fma_f32 v26, v26, v242, v244
	v_fma_f32 v27, v27, v243, v254
	v_lshlrev_b32_e32 v242, 16, v167
	v_and_b32_e32 v243, 0xffff0000, v167
	v_lshlrev_b32_e32 v244, 16, v171
	v_and_b32_e32 v254, 0xffff0000, v171
	v_fma_f32 v28, v28, v242, v244
	v_fma_f32 v29, v29, v243, v254
	v_cvt_pk_bf16_f32 v30, v30, v31
	v_cvt_pk_bf16_f32 v31, v32, v33
	v_cvt_pk_bf16_f32 v32, v26, v27
	v_cvt_pk_bf16_f32 v33, v28, v29
	s_waitcnt vmcnt(4)
	v_lshlrev_b32_e32 v242, 16, v114
	v_and_b32_e32 v243, 0xffff0000, v114
	v_lshlrev_b32_e32 v244, 16, v172
	v_and_b32_e32 v254, 0xffff0000, v172
	v_fma_f32 v22, v22, v242, v244
	v_fma_f32 v23, v23, v243, v254
	v_lshlrev_b32_e32 v242, 16, v115
	v_and_b32_e32 v243, 0xffff0000, v115
	v_lshlrev_b32_e32 v244, 16, v173
	v_and_b32_e32 v254, 0xffff0000, v173
	v_fma_f32 v24, v24, v242, v244
	v_fma_f32 v25, v25, v243, v254
	v_lshlrev_b32_e32 v242, 16, v116
	v_and_b32_e32 v243, 0xffff0000, v116
	v_lshlrev_b32_e32 v244, 16, v174
	v_and_b32_e32 v254, 0xffff0000, v174
	v_fma_f32 v18, v18, v242, v244
	v_fma_f32 v19, v19, v243, v254
	v_lshlrev_b32_e32 v242, 16, v117
	v_and_b32_e32 v243, 0xffff0000, v117
	v_lshlrev_b32_e32 v244, 16, v175
	v_and_b32_e32 v254, 0xffff0000, v175
	v_fma_f32 v20, v20, v242, v244
	v_fma_f32 v21, v21, v243, v254
	v_cvt_pk_bf16_f32 v22, v22, v23
	v_cvt_pk_bf16_f32 v23, v24, v25
	v_cvt_pk_bf16_f32 v24, v18, v19
	v_cvt_pk_bf16_f32 v25, v20, v21
	s_waitcnt vmcnt(2)
	v_lshlrev_b32_e32 v242, 16, v176
	v_and_b32_e32 v243, 0xffff0000, v176
	v_lshlrev_b32_e32 v244, 16, v106
	v_and_b32_e32 v254, 0xffff0000, v106
	v_fma_f32 v14, v14, v242, v244
	v_fma_f32 v15, v15, v243, v254
	v_lshlrev_b32_e32 v242, 16, v177
	v_and_b32_e32 v243, 0xffff0000, v177
	v_lshlrev_b32_e32 v244, 16, v107
	v_and_b32_e32 v254, 0xffff0000, v107
	v_fma_f32 v16, v16, v242, v244
	v_fma_f32 v17, v17, v243, v254
	v_lshlrev_b32_e32 v242, 16, v178
	v_and_b32_e32 v243, 0xffff0000, v178
	v_lshlrev_b32_e32 v244, 16, v108
	v_and_b32_e32 v254, 0xffff0000, v108
	v_fma_f32 v10, v10, v242, v244
	v_fma_f32 v11, v11, v243, v254
	v_lshlrev_b32_e32 v242, 16, v179
	v_and_b32_e32 v243, 0xffff0000, v179
	v_lshlrev_b32_e32 v244, 16, v109
	v_and_b32_e32 v254, 0xffff0000, v109
	v_fma_f32 v12, v12, v242, v244
	v_fma_f32 v13, v13, v243, v254
	v_cvt_pk_bf16_f32 v14, v14, v15
	v_cvt_pk_bf16_f32 v15, v16, v17
	v_cvt_pk_bf16_f32 v16, v10, v11
	v_cvt_pk_bf16_f32 v17, v12, v13
	s_waitcnt vmcnt(0)
	v_lshlrev_b32_e32 v242, 16, v180
	v_and_b32_e32 v243, 0xffff0000, v180
	v_lshlrev_b32_e32 v244, 16, v184
	v_and_b32_e32 v254, 0xffff0000, v184
	v_fma_f32 v6, v6, v242, v244
	v_fma_f32 v7, v7, v243, v254
	v_lshlrev_b32_e32 v242, 16, v181
	v_and_b32_e32 v243, 0xffff0000, v181
	v_lshlrev_b32_e32 v244, 16, v185
	v_and_b32_e32 v254, 0xffff0000, v185
	v_fma_f32 v8, v8, v242, v244
	v_fma_f32 v9, v9, v243, v254
	v_lshlrev_b32_e32 v242, 16, v182
	v_and_b32_e32 v243, 0xffff0000, v182
	v_lshlrev_b32_e32 v244, 16, v186
	v_and_b32_e32 v254, 0xffff0000, v186
	v_fma_f32 v2, v2, v242, v244
	v_fma_f32 v3, v3, v243, v254
	v_lshlrev_b32_e32 v242, 16, v183
	v_and_b32_e32 v243, 0xffff0000, v183
	v_lshlrev_b32_e32 v244, 16, v187
	v_and_b32_e32 v254, 0xffff0000, v187
	v_fma_f32 v4, v4, v242, v244
	v_fma_f32 v5, v5, v243, v254
	v_cvt_pk_bf16_f32 v6, v6, v7
	v_cvt_pk_bf16_f32 v7, v8, v9
	v_cvt_pk_bf16_f32 v8, v2, v3
	v_cvt_pk_bf16_f32 v9, v4, v5
	s_add_u32 s72, s6, 0x0
	s_addc_u32 s73, s7, 0
	global_store_dwordx4 v146, v[126:129], s[72:73] offset:0
	global_store_dwordx4 v146, v[118:121], s[72:73] offset:256
	s_add_u32 s72, s6, 0x8000
	s_addc_u32 s73, s7, 0
	global_store_dwordx4 v146, v[110:113], s[72:73] offset:0
	global_store_dwordx4 v146, v[102:105], s[72:73] offset:256
	s_add_u32 s72, s6, 0x10000
	s_addc_u32 s73, s7, 0
	global_store_dwordx4 v146, v[94:97], s[72:73] offset:0
	global_store_dwordx4 v146, v[86:89], s[72:73] offset:256
	s_add_u32 s72, s6, 0x18000
	s_addc_u32 s73, s7, 0
	global_store_dwordx4 v146, v[78:81], s[72:73] offset:0
	global_store_dwordx4 v146, v[70:73], s[72:73] offset:256
	s_add_u32 s72, s6, 0x40000
	s_addc_u32 s73, s7, 0
	global_store_dwordx4 v146, v[62:65], s[72:73] offset:0
	global_store_dwordx4 v146, v[54:57], s[72:73] offset:256
	s_add_u32 s72, s6, 0x48000
	s_addc_u32 s73, s7, 0
	global_store_dwordx4 v146, v[46:49], s[72:73] offset:0
	global_store_dwordx4 v146, v[38:41], s[72:73] offset:256
	s_add_u32 s72, s6, 0x50000
	s_addc_u32 s73, s7, 0
	global_store_dwordx4 v146, v[30:33], s[72:73] offset:0
	global_store_dwordx4 v146, v[22:25], s[72:73] offset:256
	s_add_u32 s72, s6, 0x58000
	s_addc_u32 s73, s7, 0
	global_store_dwordx4 v146, v[14:17], s[72:73] offset:0
	global_store_dwordx4 v146, v[6:9], s[72:73] offset:256
	s_cbranch_vccnz .LBB0_518
	s_andn2_b64 vcc, exec, s[8:9]
	s_cbranch_vccnz .LBB0_517
	s_barrier
	s_branch .LBB0_517
